# short-conv mixer (odd layers): prompt-row output stores made plain instead of write-through, so the rows stay in the XCD L2 for the same-XCD out-projection behind the XCC-local seam
# speedup vs baseline: 1.0052x; 1.0052x over previous
; __device__ __forceinline__ float bf_lo(unsigned w) { return __uint_as_float(w << 16); }
; __device__ __forceinline__ float bf_hi(unsigned w) { return __uint_as_float(w & 0xffff0000u); }
; __device__ __forceinline__ void sconv_phase(const Frame& F, const Args& a, int e, int zo) {
;     ...
;     for (int u = gw; u < (MP / 8) * 2; u += NGW) {
;         const int half = xal ? (u >= NGW ? 1 : 0) : (u & 1), row0 = (xal ? (u - half * NGW) : (u >> 1)) * 8, t0 = row0 & (SEQ - 1), ch = half * 512 + 8 * F.lane;
;         f32x4 wq[3][2];
; #pragma unroll
;         for (int j = 0; j < 3; ++j) { wq[j][0] = *(const f32x4*)(cw + j * D + ch); wq[j][1] = *(const f32x4*)(cw + j * D + ch + 4); }
;         f32x4 z[10][2];
; #pragma unroll
;         for (int r = 0; r < 10; ++r) { z[r][0] = (f32x4){0.f, 0.f, 0.f, 0.f}; z[r][1] = z[r][0];
;             if (t0 - 2 + r >= 0) { const v4u raw = *(const v4u*)(BGZ + (size_t)(row0 - 2 + r) * 2048 + 1024 + ch);
;                 z[r][0] = (f32x4){pg8::bf_lo(raw.x), pg8::bf_hi(raw.x), pg8::bf_lo(raw.y), pg8::bf_hi(raw.y)}; z[r][1] = (f32x4){pg8::bf_lo(raw.z), pg8::bf_hi(raw.z), pg8::bf_lo(raw.w), pg8::bf_hi(raw.w)}; } }
;         v4u graw[8];
; #pragma unroll
;         for (int i = 0; i < 8; ++i) graw[i] = *(const v4u*)(BGZ + (size_t)(row0 + i) * 2048 + ch);
; #pragma unroll
;         for (int i = 0; i < 8; ++i) { const v4u raw = graw[i];
;             const f32x4 g0 = {pg8::bf_lo(raw.x), pg8::bf_hi(raw.x), pg8::bf_lo(raw.y), pg8::bf_hi(raw.y)}, g1 = {pg8::bf_lo(raw.z), pg8::bf_hi(raw.z), pg8::bf_lo(raw.w), pg8::bf_hi(raw.w)};
;             const f32x4 y0 = g0 * (wq[0][0] * z[i][0] + wq[1][0] * z[i + 1][0] + wq[2][0] * z[i + 2][0]), y1 = g1 * (wq[0][1] * z[i][1] + wq[1][1] * z[i + 1][1] + wq[2][1] * z[i + 2][1]);
.LBB0_671:
	s_ashr_i32 s23, s22, 31
	s_lshl_b64 s[34:35], s[22:23], 12
	s_add_u32 s0, s52, s34
	s_addc_u32 s1, s53, s35
	global_load_dwordx4 v[26:29], v0, s[0:1] offset:2048
	s_or_b32 s28, s22, 1
	s_ashr_i32 s29, s28, 31
	v_lshl_add_u64 v[50:51], s[52:53], 0, v[0:1]
	s_lshl_b64 s[46:47], s[28:29], 12
	v_lshl_add_u64 v[56:57], v[50:51], 0, s[34:35]
	global_load_dwordx4 v[118:121], v[56:57], off
	s_add_u32 s0, s52, s46
	s_addc_u32 s1, s53, s47
	s_or_b32 s26, s22, 2
	s_ashr_i32 s27, s26, 31
	s_lshl_b64 s[58:59], s[26:27], 12
	v_lshl_add_u64 v[56:57], v[50:51], 0, s[46:47]
	global_load_dwordx4 v[30:33], v0, s[0:1] offset:2048
	global_load_dwordx4 v[122:125], v[56:57], off
	s_add_u32 s0, s52, s58
	s_addc_u32 s1, s53, s59
	s_or_b32 s24, s22, 3
	s_ashr_i32 s25, s24, 31
	s_lshl_b64 s[30:31], s[24:25], 12
	global_load_dwordx4 v[34:37], v0, s[0:1] offset:2048
	v_lshl_add_u64 v[56:57], v[50:51], 0, s[58:59]
	s_waitcnt vmcnt(8)
	v_pk_mul_f32 v[148:149], v[18:19], v[88:89]
	v_pk_mul_f32 v[146:147], v[20:21], v[90:91]
	v_pk_fma_f32 v[96:97], v[14:15], v[96:97], v[148:149]
	v_pk_fma_f32 v[98:99], v[16:17], v[98:99], v[146:147]
	global_load_dwordx4 v[126:129], v[56:57], off
	s_waitcnt vmcnt(5)
	v_lshlrev_b32_e32 v134, 16, v26
	v_and_b32_e32 v135, 0xffff0000, v26
	v_lshlrev_b32_e32 v136, 16, v27
	v_and_b32_e32 v137, 0xffff0000, v27
	v_lshl_add_u64 v[26:27], v[50:51], 0, s[30:31]
	global_load_dwordx4 v[130:133], v[26:27], off
	s_add_u32 s0, s52, s30
	s_addc_u32 s1, s53, s31
	global_load_dwordx4 v[38:41], v0, s[0:1] offset:2048
	s_or_b32 s20, s22, 4
	s_ashr_i32 s21, s20, 31
	s_lshl_b64 s[44:45], s[20:21], 12
	s_add_u32 s0, s52, s44
	s_addc_u32 s1, s53, s45
	s_or_b32 s18, s22, 5
	s_ashr_i32 s19, s18, 31
	s_lshl_b64 s[48:49], s[18:19], 12
	global_load_dwordx4 v[42:45], v0, s[0:1] offset:2048
	s_add_u32 s0, s52, s48
	s_addc_u32 s1, s53, s49
	s_or_b32 s16, s22, 6
	s_ashr_i32 s17, s16, 31
	s_lshl_b64 s[56:57], s[16:17], 12
	global_load_dwordx4 v[46:49], v0, s[0:1] offset:2048
	s_add_u32 s0, s52, s56
	s_addc_u32 s1, s53, s57
	s_or_b32 s14, s22, 7
	s_ashr_i32 s15, s14, 31
	global_load_dwordx4 v[52:55], v0, s[0:1] offset:2048
	s_lshl_b64 s[0:1], s[14:15], 12
	s_add_u32 s40, s52, s0
	s_addc_u32 s41, s53, s1
	v_lshl_add_u64 v[26:27], v[50:51], 0, s[44:45]
	global_load_dwordx4 v[66:69], v0, s[40:41] offset:2048
	v_lshlrev_b32_e32 v138, 16, v28
	v_and_b32_e32 v139, 0xffff0000, v28
	v_lshlrev_b32_e32 v140, 16, v29
	v_and_b32_e32 v141, 0xffff0000, v29
	s_waitcnt vmcnt(7)
	v_lshlrev_b32_e32 v104, 16, v34
	v_and_b32_e32 v105, 0xffff0000, v34
	v_lshlrev_b32_e32 v106, 16, v35
	v_and_b32_e32 v107, 0xffff0000, v35
	v_lshlrev_b32_e32 v100, 16, v36
	v_and_b32_e32 v101, 0xffff0000, v36
	v_lshlrev_b32_e32 v102, 16, v37
	v_and_b32_e32 v103, 0xffff0000, v37
	v_lshl_add_u64 v[28:29], v[50:51], 0, s[48:49]
	v_lshlrev_b32_e32 v112, 16, v30
	v_and_b32_e32 v113, 0xffff0000, v30
	v_lshlrev_b32_e32 v114, 16, v31
	v_and_b32_e32 v115, 0xffff0000, v31
	v_lshlrev_b32_e32 v108, 16, v32
	v_and_b32_e32 v109, 0xffff0000, v32
	v_lshlrev_b32_e32 v110, 16, v33
	v_and_b32_e32 v111, 0xffff0000, v33
	v_lshlrev_b32_e32 v142, 16, v118
	v_and_b32_e32 v143, 0xffff0000, v118
	v_pk_fma_f32 v[96:97], v[22:23], v[134:135], v[96:97]
	v_lshlrev_b32_e32 v118, 16, v119
	v_and_b32_e32 v119, 0xffff0000, v119
	v_pk_fma_f32 v[98:99], v[24:25], v[136:137], v[98:99]
	v_pk_mul_f32 v[96:97], v[96:97], v[142:143]
	v_pk_mul_f32 v[142:143], v[8:9], v[78:79]
	v_pk_mul_f32 v[98:99], v[98:99], v[118:119]
	v_pk_mul_f32 v[118:119], v[6:7], v[58:59]
	v_pk_fma_f32 v[86:87], v[4:5], v[86:87], v[142:143]
	v_lshlrev_b32_e32 v144, 16, v120
	v_and_b32_e32 v145, 0xffff0000, v120
	v_lshlrev_b32_e32 v120, 16, v121
	v_and_b32_e32 v121, 0xffff0000, v121
	v_pk_fma_f32 v[80:81], v[2:3], v[80:81], v[118:119]
	v_pk_fma_f32 v[86:87], v[12:13], v[140:141], v[86:87]
	v_pk_fma_f32 v[80:81], v[10:11], v[138:139], v[80:81]
	v_pk_mul_f32 v[86:87], v[86:87], v[120:121]
	v_pk_mul_f32 v[120:121], v[20:21], v[136:137]
	v_pk_mul_f32 v[80:81], v[80:81], v[144:145]
	v_pk_mul_f32 v[118:119], v[18:19], v[134:135]
	v_pk_fma_f32 v[90:91], v[16:17], v[90:91], v[120:121]
	v_cvt_pk_bf16_f32 v96, v96, v97
	v_cvt_pk_bf16_f32 v97, v98, v99
	v_cvt_pk_bf16_f32 v98, v80, v81
	v_cvt_pk_bf16_f32 v99, v86, v87
	v_lshlrev_b32_e32 v86, 16, v123
	v_and_b32_e32 v87, 0xffff0000, v123
	v_pk_fma_f32 v[88:89], v[14:15], v[88:89], v[118:119]
	v_pk_fma_f32 v[90:91], v[24:25], v[114:115], v[90:91]
	v_pk_fma_f32 v[88:89], v[22:23], v[112:113], v[88:89]
	v_pk_mul_f32 v[86:87], v[90:91], v[86:87]
	s_waitcnt vmcnt(4)
; __device__ __forceinline__ float bf_lo(unsigned w) { return __uint_as_float(w << 16); }
; __device__ __forceinline__ float bf_hi(unsigned w) { return __uint_as_float(w & 0xffff0000u); }
; __device__ __forceinline__ unsigned pk2(float lo, float hi) { const f32x2_cv v = {lo, hi}; const bf16x2_cv b = __builtin_convertvector(v, bf16x2_cv); return __builtin_bit_cast(unsigned, b); }
; __device__ __forceinline__ void st16_wt(void* p, f32x4 v) { asm volatile("global_store_dwordx4 %0, %1, off sc1\n\ts_nop 1" :: "v"(p), "v"(v) : "memory"); }
; __device__ __forceinline__ void sconv_phase(const Frame& F, const Args& a, int e, int zo) {
;     ...
;             if (t0 - 2 + r >= 0) { const v4u raw = *(const v4u*)(BGZ + (size_t)(row0 - 2 + r) * 2048 + 1024 + ch);
;                 z[r][0] = (f32x4){pg8::bf_lo(raw.x), pg8::bf_hi(raw.x), pg8::bf_lo(raw.y), pg8::bf_hi(raw.y)}; z[r][1] = (f32x4){pg8::bf_lo(raw.z), pg8::bf_hi(raw.z), pg8::bf_lo(raw.w), pg8::bf_hi(raw.w)}; } }
;         v4u graw[8];
; #pragma unroll
;         for (int i = 0; i < 8; ++i) graw[i] = *(const v4u*)(BGZ + (size_t)(row0 + i) * 2048 + ch);
; #pragma unroll
;         for (int i = 0; i < 8; ++i) { const v4u raw = graw[i];
;             const f32x4 g0 = {pg8::bf_lo(raw.x), pg8::bf_hi(raw.x), pg8::bf_lo(raw.y), pg8::bf_hi(raw.y)}, g1 = {pg8::bf_lo(raw.z), pg8::bf_hi(raw.z), pg8::bf_lo(raw.w), pg8::bf_hi(raw.w)};
;             const f32x4 y0 = g0 * (wq[0][0] * z[i][0] + wq[1][0] * z[i + 1][0] + wq[2][0] * z[i + 2][0]), y1 = g1 * (wq[0][1] * z[i][1] + wq[1][1] * z[i + 1][1] + wq[2][1] * z[i + 2][1]);
;             { const v4u o_ = (v4u){pk2(y0[0], y0[1]), pk2(y0[2], y0[3]), pk2(y1[0], y1[1]), pk2(y1[2], y1[3])}; st16_wt(A2 + (size_t)(row0 + i) * D + ch, __builtin_bit_cast(f32x4, o_)); } }
	v_lshlrev_b32_e32 v92, 16, v38
	v_and_b32_e32 v93, 0xffff0000, v38
	v_lshlrev_b32_e32 v94, 16, v39
	v_and_b32_e32 v95, 0xffff0000, v39
	v_lshlrev_b32_e32 v82, 16, v40
	v_and_b32_e32 v83, 0xffff0000, v40
	v_lshlrev_b32_e32 v84, 16, v41
	v_and_b32_e32 v85, 0xffff0000, v41
	global_load_dwordx4 v[38:41], v[26:27], off
	global_load_dwordx4 v[34:37], v[28:29], off
	v_lshl_add_u64 v[26:27], v[50:51], 0, s[56:57]
	v_lshl_add_u64 v[28:29], v[50:51], 0, s[0:1]
	global_load_dwordx4 v[30:33], v[26:27], off
	s_nop 0
	global_load_dwordx4 v[26:29], v[28:29], off
	v_lshl_add_u64 v[50:51], s[84:85], 0, v[0:1]
	s_lshl_b64 s[0:1], s[22:23], 11
	v_lshl_add_u64 v[80:81], v[50:51], 0, s[0:1]
	global_store_dwordx4 v[80:81], v[96:99], off
	s_nop 1
	v_lshlrev_b32_e32 v80, 16, v122
	v_and_b32_e32 v81, 0xffff0000, v122
	v_pk_mul_f32 v[90:91], v[8:9], v[140:141]
	v_pk_mul_f32 v[80:81], v[88:89], v[80:81]
	v_pk_mul_f32 v[88:89], v[6:7], v[138:139]
	v_pk_fma_f32 v[78:79], v[4:5], v[78:79], v[90:91]
	v_lshlrev_b32_e32 v98, 16, v125
	v_and_b32_e32 v99, 0xffff0000, v125
	v_pk_fma_f32 v[58:59], v[2:3], v[58:59], v[88:89]
	v_pk_fma_f32 v[78:79], v[12:13], v[110:111], v[78:79]
	v_lshlrev_b32_e32 v96, 16, v124
	v_and_b32_e32 v97, 0xffff0000, v124
	v_pk_fma_f32 v[58:59], v[10:11], v[108:109], v[58:59]
	v_pk_mul_f32 v[88:89], v[78:79], v[98:99]
	v_pk_mul_f32 v[58:59], v[58:59], v[96:97]
	v_cvt_pk_bf16_f32 v78, v80, v81
	v_cvt_pk_bf16_f32 v81, v88, v89
	s_lshl_b64 s[0:1], s[28:29], 11
	v_pk_mul_f32 v[88:89], v[18:19], v[112:113]
	v_pk_mul_f32 v[90:91], v[20:21], v[114:115]
	v_cvt_pk_bf16_f32 v79, v86, v87
	v_cvt_pk_bf16_f32 v80, v58, v59
	v_lshl_add_u64 v[58:59], v[50:51], 0, s[0:1]
	v_pk_fma_f32 v[90:91], v[16:17], v[136:137], v[90:91]
	v_pk_fma_f32 v[88:89], v[14:15], v[134:135], v[88:89]
	global_store_dwordx4 v[58:59], v[78:81], off
	s_nop 1
	v_lshlrev_b32_e32 v58, 16, v126
	v_and_b32_e32 v59, 0xffff0000, v126
	v_lshlrev_b32_e32 v78, 16, v127
	v_and_b32_e32 v79, 0xffff0000, v127
	v_pk_fma_f32 v[88:89], v[22:23], v[104:105], v[88:89]
	v_pk_fma_f32 v[90:91], v[24:25], v[106:107], v[90:91]
	v_pk_mul_f32 v[58:59], v[88:89], v[58:59]
	v_pk_mul_f32 v[90:91], v[90:91], v[78:79]
	v_pk_mul_f32 v[78:79], v[6:7], v[108:109]
	v_pk_mul_f32 v[88:89], v[8:9], v[110:111]
	v_pk_fma_f32 v[78:79], v[2:3], v[138:139], v[78:79]
	v_pk_fma_f32 v[88:89], v[4:5], v[140:141], v[88:89]
	v_lshlrev_b32_e32 v80, 16, v128
	v_and_b32_e32 v81, 0xffff0000, v128
	v_lshlrev_b32_e32 v86, 16, v129
	v_and_b32_e32 v87, 0xffff0000, v129
	v_pk_fma_f32 v[78:79], v[10:11], v[100:101], v[78:79]
	v_pk_fma_f32 v[88:89], v[12:13], v[102:103], v[88:89]
	v_pk_mul_f32 v[80:81], v[78:79], v[80:81]
	v_pk_mul_f32 v[86:87], v[88:89], v[86:87]
	v_cvt_pk_bf16_f32 v79, v90, v91
	s_lshl_b64 s[0:1], s[26:27], 11
	v_pk_mul_f32 v[88:89], v[18:19], v[104:105]
	v_pk_mul_f32 v[90:91], v[20:21], v[106:107]
	v_cvt_pk_bf16_f32 v78, v58, v59
	v_lshl_add_u64 v[58:59], v[50:51], 0, s[0:1]
	v_pk_fma_f32 v[90:91], v[16:17], v[114:115], v[90:91]
	v_pk_fma_f32 v[88:89], v[14:15], v[112:113], v[88:89]
	v_cvt_pk_bf16_f32 v80, v80, v81
	v_cvt_pk_bf16_f32 v81, v86, v87
	global_store_dwordx4 v[58:59], v[78:81], off
	s_nop 1
	v_lshlrev_b32_e32 v58, 16, v130
	v_and_b32_e32 v59, 0xffff0000, v130
	v_lshlrev_b32_e32 v78, 16, v131
	v_and_b32_e32 v79, 0xffff0000, v131
	v_pk_fma_f32 v[88:89], v[22:23], v[92:93], v[88:89]
	v_pk_fma_f32 v[90:91], v[24:25], v[94:95], v[90:91]
	v_pk_mul_f32 v[58:59], v[88:89], v[58:59]
	v_pk_mul_f32 v[90:91], v[90:91], v[78:79]
	v_pk_mul_f32 v[78:79], v[6:7], v[100:101]
	v_pk_mul_f32 v[88:89], v[8:9], v[102:103]
	v_pk_fma_f32 v[78:79], v[2:3], v[108:109], v[78:79]
	v_pk_fma_f32 v[88:89], v[4:5], v[110:111], v[88:89]
	v_lshlrev_b32_e32 v80, 16, v132
	v_and_b32_e32 v81, 0xffff0000, v132
	v_lshlrev_b32_e32 v86, 16, v133
	v_and_b32_e32 v87, 0xffff0000, v133
	v_pk_fma_f32 v[78:79], v[10:11], v[82:83], v[78:79]
	v_pk_fma_f32 v[88:89], v[12:13], v[84:85], v[88:89]
	v_pk_mul_f32 v[80:81], v[78:79], v[80:81]
	v_pk_mul_f32 v[86:87], v[88:89], v[86:87]
	v_cvt_pk_bf16_f32 v80, v80, v81
	v_cvt_pk_bf16_f32 v81, v86, v87
	s_lshl_b64 s[0:1], s[24:25], 11
	v_cvt_pk_bf16_f32 v78, v58, v59
	v_cvt_pk_bf16_f32 v79, v90, v91
	v_lshl_add_u64 v[58:59], v[50:51], 0, s[0:1]
	global_store_dwordx4 v[58:59], v[78:81], off
	s_nop 1
	v_pk_mul_f32 v[80:81], v[18:19], v[92:93]
	v_pk_mul_f32 v[86:87], v[20:21], v[94:95]
	s_waitcnt vmcnt(7)
	v_lshlrev_b32_e32 v74, 16, v42
	v_and_b32_e32 v75, 0xffff0000, v42
	v_lshlrev_b32_e32 v76, 16, v43
	v_and_b32_e32 v77, 0xffff0000, v43
	v_pk_fma_f32 v[86:87], v[16:17], v[106:107], v[86:87]
	v_pk_fma_f32 v[80:81], v[14:15], v[104:105], v[80:81]
	s_waitcnt vmcnt(3)
; __device__ __forceinline__ float bf_lo(unsigned w) { return __uint_as_float(w << 16); }
; __device__ __forceinline__ float bf_hi(unsigned w) { return __uint_as_float(w & 0xffff0000u); }
; __device__ __forceinline__ unsigned pk2(float lo, float hi) { const f32x2_cv v = {lo, hi}; const bf16x2_cv b = __builtin_convertvector(v, bf16x2_cv); return __builtin_bit_cast(unsigned, b); }
; __device__ __forceinline__ void st16_wt(void* p, f32x4 v) { asm volatile("global_store_dwordx4 %0, %1, off sc1\n\ts_nop 1" :: "v"(p), "v"(v) : "memory"); }
; __device__ __forceinline__ void sconv_phase(const Frame& F, const Args& a, int e, int zo) {
;     ...
;         v4u graw[8];
; #pragma unroll
;         for (int i = 0; i < 8; ++i) graw[i] = *(const v4u*)(BGZ + (size_t)(row0 + i) * 2048 + ch);
; #pragma unroll
;         for (int i = 0; i < 8; ++i) { const v4u raw = graw[i];
;             const f32x4 g0 = {pg8::bf_lo(raw.x), pg8::bf_hi(raw.x), pg8::bf_lo(raw.y), pg8::bf_hi(raw.y)}, g1 = {pg8::bf_lo(raw.z), pg8::bf_hi(raw.z), pg8::bf_lo(raw.w), pg8::bf_hi(raw.w)};
;             const f32x4 y0 = g0 * (wq[0][0] * z[i][0] + wq[1][0] * z[i + 1][0] + wq[2][0] * z[i + 2][0]), y1 = g1 * (wq[0][1] * z[i][1] + wq[1][1] * z[i + 1][1] + wq[2][1] * z[i + 2][1]);
;             { const v4u o_ = (v4u){pk2(y0[0], y0[1]), pk2(y0[2], y0[3]), pk2(y1[0], y1[1]), pk2(y1[2], y1[3])}; st16_wt(A2 + (size_t)(row0 + i) * D + ch, __builtin_bit_cast(f32x4, o_)); } }
;     }
	v_lshlrev_b32_e32 v58, 16, v38
	v_and_b32_e32 v59, 0xffff0000, v38
	v_lshlrev_b32_e32 v38, 16, v39
	v_and_b32_e32 v39, 0xffff0000, v39
	v_pk_fma_f32 v[80:81], v[22:23], v[74:75], v[80:81]
	v_pk_fma_f32 v[86:87], v[24:25], v[76:77], v[86:87]
	v_lshlrev_b32_e32 v70, 16, v44
	v_pk_mul_f32 v[86:87], v[86:87], v[38:39]
	v_pk_mul_f32 v[38:39], v[80:81], v[58:59]
	v_pk_mul_f32 v[58:59], v[6:7], v[82:83]
	v_pk_mul_f32 v[80:81], v[8:9], v[84:85]
	v_and_b32_e32 v71, 0xffff0000, v44
	v_lshlrev_b32_e32 v72, 16, v45
	v_and_b32_e32 v73, 0xffff0000, v45
	v_pk_fma_f32 v[80:81], v[4:5], v[102:103], v[80:81]
	v_pk_fma_f32 v[58:59], v[2:3], v[100:101], v[58:59]
	v_lshlrev_b32_e32 v78, 16, v40
	v_and_b32_e32 v79, 0xffff0000, v40
	v_lshlrev_b32_e32 v40, 16, v41
	v_and_b32_e32 v41, 0xffff0000, v41
	v_pk_fma_f32 v[58:59], v[10:11], v[70:71], v[58:59]
	v_pk_fma_f32 v[80:81], v[12:13], v[72:73], v[80:81]
	s_lshl_b64 s[0:1], s[20:21], 11
	v_pk_mul_f32 v[80:81], v[80:81], v[40:41]
	v_pk_mul_f32 v[40:41], v[58:59], v[78:79]
	v_lshl_add_u64 v[58:59], v[50:51], 0, s[0:1]
	v_cvt_pk_bf16_f32 v38, v38, v39
	v_cvt_pk_bf16_f32 v39, v86, v87
	v_cvt_pk_bf16_f32 v40, v40, v41
	v_cvt_pk_bf16_f32 v41, v80, v81
	global_store_dwordx4 v[58:59], v[38:41], off
	s_nop 1
	v_pk_mul_f32 v[58:59], v[18:19], v[74:75]
	v_pk_mul_f32 v[78:79], v[20:21], v[76:77]
	v_lshlrev_b32_e32 v56, 16, v46
	v_and_b32_e32 v57, 0xffff0000, v46
	v_lshlrev_b32_e32 v60, 16, v47
	v_and_b32_e32 v61, 0xffff0000, v47
	v_pk_fma_f32 v[78:79], v[16:17], v[94:95], v[78:79]
	v_pk_fma_f32 v[58:59], v[14:15], v[92:93], v[58:59]
	s_waitcnt vmcnt(2)
	v_lshlrev_b32_e32 v38, 16, v34
	v_and_b32_e32 v39, 0xffff0000, v34
	v_lshlrev_b32_e32 v34, 16, v35
	v_and_b32_e32 v35, 0xffff0000, v35
	v_pk_fma_f32 v[58:59], v[22:23], v[56:57], v[58:59]
	v_pk_fma_f32 v[78:79], v[24:25], v[60:61], v[78:79]
	v_lshlrev_b32_e32 v42, 16, v48
	v_pk_mul_f32 v[78:79], v[78:79], v[34:35]
	v_pk_mul_f32 v[34:35], v[58:59], v[38:39]
	v_pk_mul_f32 v[38:39], v[6:7], v[70:71]
	v_pk_mul_f32 v[58:59], v[8:9], v[72:73]
	v_and_b32_e32 v43, 0xffff0000, v48
	v_lshlrev_b32_e32 v44, 16, v49
	v_and_b32_e32 v45, 0xffff0000, v49
	v_pk_fma_f32 v[58:59], v[4:5], v[84:85], v[58:59]
	v_pk_fma_f32 v[38:39], v[2:3], v[82:83], v[38:39]
	v_lshlrev_b32_e32 v40, 16, v36
	v_and_b32_e32 v41, 0xffff0000, v36
	v_lshlrev_b32_e32 v36, 16, v37
	v_and_b32_e32 v37, 0xffff0000, v37
	v_pk_fma_f32 v[38:39], v[10:11], v[42:43], v[38:39]
	v_pk_fma_f32 v[58:59], v[12:13], v[44:45], v[58:59]
	s_lshl_b64 s[0:1], s[18:19], 11
	v_pk_mul_f32 v[58:59], v[58:59], v[36:37]
	v_pk_mul_f32 v[36:37], v[38:39], v[40:41]
	v_lshl_add_u64 v[38:39], v[50:51], 0, s[0:1]
	v_cvt_pk_bf16_f32 v34, v34, v35
	v_cvt_pk_bf16_f32 v35, v78, v79
	v_cvt_pk_bf16_f32 v36, v36, v37
	v_cvt_pk_bf16_f32 v37, v58, v59
	global_store_dwordx4 v[38:39], v[34:37], off
	s_nop 1
	v_pk_mul_f32 v[38:39], v[18:19], v[56:57]
	v_pk_mul_f32 v[40:41], v[20:21], v[60:61]
	v_lshlrev_b32_e32 v62, 16, v52
	v_and_b32_e32 v63, 0xffff0000, v52
	v_lshlrev_b32_e32 v64, 16, v53
	v_and_b32_e32 v65, 0xffff0000, v53
	v_pk_fma_f32 v[40:41], v[16:17], v[76:77], v[40:41]
	v_pk_fma_f32 v[38:39], v[14:15], v[74:75], v[38:39]
	s_waitcnt vmcnt(1)
	v_lshlrev_b32_e32 v34, 16, v30
	v_and_b32_e32 v35, 0xffff0000, v30
	v_lshlrev_b32_e32 v30, 16, v31
	v_and_b32_e32 v31, 0xffff0000, v31
	v_pk_fma_f32 v[38:39], v[22:23], v[62:63], v[38:39]
	v_pk_fma_f32 v[40:41], v[24:25], v[64:65], v[40:41]
	v_lshlrev_b32_e32 v52, 16, v54
	v_pk_mul_f32 v[40:41], v[40:41], v[30:31]
	v_pk_mul_f32 v[30:31], v[38:39], v[34:35]
	v_pk_mul_f32 v[34:35], v[6:7], v[42:43]
	v_pk_mul_f32 v[38:39], v[8:9], v[44:45]
	v_and_b32_e32 v53, 0xffff0000, v54
	v_lshlrev_b32_e32 v54, 16, v55
	v_and_b32_e32 v55, 0xffff0000, v55
	v_pk_fma_f32 v[38:39], v[4:5], v[72:73], v[38:39]
	v_pk_fma_f32 v[34:35], v[2:3], v[70:71], v[34:35]
	v_lshlrev_b32_e32 v36, 16, v32
	v_and_b32_e32 v37, 0xffff0000, v32
	v_lshlrev_b32_e32 v32, 16, v33
	v_and_b32_e32 v33, 0xffff0000, v33
	v_pk_fma_f32 v[34:35], v[10:11], v[52:53], v[34:35]
	v_pk_fma_f32 v[38:39], v[12:13], v[54:55], v[38:39]
	v_pk_mul_f32 v[18:19], v[18:19], v[62:63]
	v_pk_mul_f32 v[38:39], v[38:39], v[32:33]
	v_pk_mul_f32 v[32:33], v[34:35], v[36:37]
	v_pk_mul_f32 v[20:21], v[20:21], v[64:65]
	v_pk_mul_f32 v[6:7], v[6:7], v[52:53]
	v_pk_mul_f32 v[8:9], v[8:9], v[54:55]
	v_lshlrev_b32_e32 v48, 16, v68
	v_and_b32_e32 v49, 0xffff0000, v68
	v_lshlrev_b32_e32 v46, 16, v69
	v_and_b32_e32 v47, 0xffff0000, v69
	v_lshlrev_b32_e32 v68, 16, v66
	v_and_b32_e32 v69, 0xffff0000, v66
	v_lshlrev_b32_e32 v66, 16, v67
	v_and_b32_e32 v67, 0xffff0000, v67
	v_cvt_pk_bf16_f32 v30, v30, v31
	v_cvt_pk_bf16_f32 v31, v40, v41
	v_cvt_pk_bf16_f32 v32, v32, v33
	v_cvt_pk_bf16_f32 v33, v38, v39
	s_lshl_b64 s[0:1], s[16:17], 11
	v_pk_fma_f32 v[16:17], v[16:17], v[60:61], v[20:21]
	v_pk_fma_f32 v[14:15], v[14:15], v[56:57], v[18:19]
	v_pk_fma_f32 v[4:5], v[4:5], v[44:45], v[8:9]
	v_pk_fma_f32 v[2:3], v[2:3], v[42:43], v[6:7]
	v_lshl_add_u64 v[34:35], v[50:51], 0, s[0:1]
	global_store_dwordx4 v[34:35], v[30:33], off
	s_nop 1
	s_waitcnt vmcnt(0)
	v_lshlrev_b32_e32 v30, 16, v26
	v_and_b32_e32 v31, 0xffff0000, v26
	v_lshlrev_b32_e32 v26, 16, v27
	v_and_b32_e32 v27, 0xffff0000, v27
	v_lshlrev_b32_e32 v32, 16, v28
	v_and_b32_e32 v33, 0xffff0000, v28
	v_lshlrev_b32_e32 v28, 16, v29
	v_and_b32_e32 v29, 0xffff0000, v29
	v_pk_fma_f32 v[14:15], v[22:23], v[68:69], v[14:15]
	v_pk_fma_f32 v[16:17], v[24:25], v[66:67], v[16:17]
	v_pk_fma_f32 v[2:3], v[10:11], v[48:49], v[2:3]
	v_pk_fma_f32 v[4:5], v[12:13], v[46:47], v[4:5]
	v_pk_mul_f32 v[16:17], v[16:17], v[26:27]
	v_pk_mul_f32 v[14:15], v[14:15], v[30:31]
	v_pk_mul_f32 v[6:7], v[4:5], v[28:29]
	v_pk_mul_f32 v[4:5], v[2:3], v[32:33]
	s_lshl_b64 s[0:1], s[14:15], 11
	v_cvt_pk_bf16_f32 v2, v14, v15
	v_cvt_pk_bf16_f32 v3, v16, v17
	v_cvt_pk_bf16_f32 v4, v4, v5
	v_cvt_pk_bf16_f32 v5, v6, v7
	v_lshl_add_u64 v[6:7], v[50:51], 0, s[0:1]
	global_store_dwordx4 v[6:7], v[2:5], off
	s_nop 1
	s_add_i32 s2, s2, s92
	s_cmpk_gt_i32 s2, 0xfff
	s_cbranch_scc1 .LBB0_676
